# MLA softmax stream cleanup: exp in place, pk row sums, no register shuffles (-41 VALU per iteration)
# baseline (speedup 1.0000x reference)
.LBB0_2719:
	v_exp_f32_e32 v196, v48
	v_exp_f32_e32 v197, v49
	s_waitcnt lgkmcnt(5)
	v_mfma_f32_32x32x16_bf16 v[80:95], v[228:231], v[116:119], v[80:95]
	ds_read_b128 v[228:231], v227 offset:6784
	v_exp_f32_e32 v198, v50
	v_exp_f32_e32 v199, v51
	s_waitcnt lgkmcnt(5)
	v_mfma_f32_32x32x16_bf16 v[80:95], v[232:235], v[120:123], v[80:95]
	ds_read_b128 v[232:235], v227 offset:6816
	v_exp_f32_e32 v200, v52
	v_exp_f32_e32 v201, v53
	s_waitcnt lgkmcnt(5)
	v_mfma_f32_32x32x16_bf16 v[64:79], v[236:239], v[100:103], v[160:175]
	v_exp_f32_e32 v202, v54
	v_exp_f32_e32 v203, v55
	s_waitcnt lgkmcnt(4)
	v_mfma_f32_32x32x16_bf16 v[64:79], v[240:243], v[104:107], v[64:79]
	v_exp_f32_e32 v204, v56
	v_exp_f32_e32 v205, v57
	s_waitcnt lgkmcnt(3)
	v_mfma_f32_32x32x16_bf16 v[64:79], v[244:247], v[108:111], v[64:79]
	v_exp_f32_e32 v206, v58
	s_waitcnt lgkmcnt(2)
	v_mfma_f32_32x32x16_bf16 v[64:79], v[248:251], v[112:115], v[64:79]
	s_mul_i32 s20, s12, 0x2400
	v_exp_f32_e32 v207, v59
	v_exp_f32_e32 v212, v32
	s_waitcnt lgkmcnt(1)
	v_mfma_f32_32x32x16_bf16 v[64:79], v[228:231], v[116:119], v[64:79]
	v_lshlrev_b32_e32 v193, 1, v185
	v_lshlrev_b32_e32 v96, 1, v253
	v_exp_f32_e32 v208, v60
	s_waitcnt lgkmcnt(0)
	v_mfma_f32_32x32x16_bf16 v[64:79], v[232:235], v[120:123], v[64:79]
	v_add3_u32 v52, s20, v193, v96
	v_exp_f32_e32 v209, v61
	v_add_u32_e32 v58, 0xa800, v52
	v_exp_f32_e32 v210, v62
	v_add_u32_e32 v56, 0x9800, v52
	ds_read_b64 v[52:53], v58 offset:1536
	ds_read_b64 v[54:55], v58 offset:1552
	v_exp_f32_e32 v211, v63
	ds_read_b64 v[48:49], v56 offset:1024
	ds_read_b64 v[50:51], v56 offset:1040
	v_exp_f32_e32 v213, v33
	v_exp_f32_e32 v216, v36
	v_exp_f32_e32 v214, v34
	v_exp_f32_e32 v215, v35
	v_cvt_pk_bf16_f32 v32, v196, v197
	v_cvt_pk_bf16_f32 v33, v198, v199
	v_cvt_pk_bf16_f32 v34, v200, v201
	v_cvt_pk_bf16_f32 v35, v202, v203
	v_exp_f32_e32 v217, v37
	s_waitcnt lgkmcnt(2)
	v_mfma_f32_32x32x16_bf16 v[0:15], v[52:55], v[32:35], v[0:15]
	v_exp_f32_e32 v218, v38
	v_exp_f32_e32 v219, v39
	ds_read_b64 v[36:37], v58 offset:1568
	ds_read_b64 v[38:39], v58 offset:1584
	v_exp_f32_e32 v220, v40
	s_waitcnt lgkmcnt(2)
	v_mfma_f32_32x32x16_bf16 v[16:31], v[48:51], v[32:35], v[16:31]
	ds_read_b64 v[48:49], v56 offset:1056
	ds_read_b64 v[50:51], v56 offset:1072
	v_cvt_pk_bf16_f32 v32, v204, v205
	v_cvt_pk_bf16_f32 v33, v206, v207
	v_cvt_pk_bf16_f32 v34, v208, v209
	v_cvt_pk_bf16_f32 v35, v210, v211
	v_exp_f32_e32 v221, v41
	s_waitcnt lgkmcnt(2)
	v_mfma_f32_32x32x16_bf16 v[0:15], v[36:39], v[32:35], v[0:15]
	ds_read_b64 v[36:37], v58 offset:1600
	ds_read_b64 v[38:39], v58 offset:1616
	v_exp_f32_e32 v222, v42
	v_exp_f32_e32 v223, v43
	v_exp_f32_e32 v224, v44
	s_waitcnt lgkmcnt(2)
	v_mfma_f32_32x32x16_bf16 v[16:31], v[48:51], v[32:35], v[16:31]
	ds_read_b64 v[48:49], v56 offset:1088
	ds_read_b64 v[50:51], v56 offset:1104
	v_cvt_pk_bf16_f32 v32, v212, v213
	v_cvt_pk_bf16_f32 v33, v214, v215
	v_cvt_pk_bf16_f32 v34, v216, v217
	v_cvt_pk_bf16_f32 v35, v218, v219
	v_exp_f32_e32 v225, v45
	ds_read_b64 v[40:41], v56 offset:1120
	ds_read_b64 v[42:43], v56 offset:1136
	s_waitcnt lgkmcnt(4)
	v_mfma_f32_32x32x16_bf16 v[0:15], v[36:39], v[32:35], v[0:15]
	ds_read_b64 v[36:37], v58 offset:1632
	ds_read_b64 v[38:39], v58 offset:1648
	v_exp_f32_e32 v226, v46
	s_add_i32 s4, s16, -4
	s_cmp_ge_u32 s4, s9
	s_waitcnt lgkmcnt(0)
	s_barrier
	v_mfma_f32_32x32x16_bf16 v[16:31], v[48:51], v[32:35], v[16:31]
	v_exp_f32_e32 v227, v47
	v_cvt_pk_bf16_f32 v32, v220, v221
	v_cvt_pk_bf16_f32 v33, v222, v223
	v_cvt_pk_bf16_f32 v34, v224, v225
	v_cvt_pk_bf16_f32 v35, v226, v227
	s_nop 1
	v_mfma_f32_32x32x16_bf16 v[16:31], v[40:43], v[32:35], v[16:31]
	v_mfma_f32_32x32x16_bf16 v[0:15], v[36:39], v[32:35], v[0:15]
	s_cbranch_scc1 .LBB0_2726
	s_mul_i32 s21, s12, 0x3400
	v_add_u32_e32 v32, s21, v179
	s_waitcnt vmcnt(1)
	ds_write_b128 v32, v[128:131]
	s_and_saveexec_b64 s[4:5], s[10:11]
	v_add_u32_e32 v32, s21, v177
	ds_write_b128 v32, v[124:127]
	s_or_b64 exec, exec, s[4:5]
	v_lshlrev_b32_e32 v32, 1, v182
	v_add3_u32 v32, s20, v32, v158
	s_cmp_ge_u32 s16, s8
	s_waitcnt vmcnt(0)
	ds_write_b128 v32, v[132:135] offset:39936
	s_cbranch_scc1 .LBB0_2726
	global_load_dwordx4 v[128:131], v178, s[98:99]
	s_and_saveexec_b64 s[4:5], s[10:11]
	s_cbranch_execz .LBB0_2725
	global_load_dwordx4 v[124:127], v176, s[98:99]

.LBB0_2726:
	v_add_u32_e32 v191, s19, v184
	ds_read_b128 v[236:239], v191
	ds_read_b128 v[240:243], v191 offset:32
	ds_read_b128 v[244:247], v191 offset:64
	ds_read_b128 v[248:251], v191 offset:96
	ds_read_b128 v[228:231], v191 offset:128
	ds_read_b128 v[232:235], v191 offset:160
.LBB0_2728:
	v_pk_add_f32 v[196:197], v[196:197], v[198:199]
	v_pk_add_f32 v[200:201], v[200:201], v[202:203]
	s_waitcnt lgkmcnt(5)
	v_mfma_f32_32x32x16_bf16 v[48:63], v[236:239], v[100:103], v[160:175]
	ds_read_b128 v[236:239], v191 offset:6656
	v_pk_add_f32 v[196:197], v[196:197], v[204:205]
	v_pk_add_f32 v[200:201], v[200:201], v[206:207]
	s_waitcnt lgkmcnt(5)
	v_mfma_f32_32x32x16_bf16 v[48:63], v[240:243], v[104:107], v[48:63]
	ds_read_b128 v[240:243], v191 offset:6688
	v_pk_add_f32 v[196:197], v[196:197], v[208:209]
	v_pk_add_f32 v[200:201], v[200:201], v[210:211]
	s_waitcnt lgkmcnt(5)
	v_mfma_f32_32x32x16_bf16 v[48:63], v[244:247], v[108:111], v[48:63]
	ds_read_b128 v[244:247], v191 offset:6720
	v_pk_add_f32 v[196:197], v[196:197], v[212:213]
	v_pk_add_f32 v[200:201], v[200:201], v[214:215]
	s_waitcnt lgkmcnt(5)
	v_mfma_f32_32x32x16_bf16 v[48:63], v[248:251], v[112:115], v[48:63]
	ds_read_b128 v[248:251], v191 offset:6752
	v_pk_add_f32 v[196:197], v[196:197], v[216:217]
	v_pk_add_f32 v[200:201], v[200:201], v[218:219]
	s_waitcnt lgkmcnt(5)
	v_mfma_f32_32x32x16_bf16 v[48:63], v[228:231], v[116:119], v[48:63]
	ds_read_b128 v[228:231], v191 offset:6784
	v_pk_add_f32 v[196:197], v[196:197], v[220:221]
	v_pk_add_f32 v[200:201], v[200:201], v[222:223]
	s_waitcnt lgkmcnt(5)
	v_mfma_f32_32x32x16_bf16 v[48:63], v[232:235], v[120:123], v[48:63]
	ds_read_b128 v[232:235], v191 offset:6816
	v_pk_add_f32 v[196:197], v[196:197], v[224:225]
	v_pk_add_f32 v[200:201], v[200:201], v[226:227]
	s_waitcnt lgkmcnt(5)
	v_mfma_f32_32x32x16_bf16 v[32:47], v[236:239], v[100:103], v[160:175]
	v_pk_add_f32 v[196:197], v[196:197], v[200:201]
	v_add_f32_e32 v195, v196, v197
	s_waitcnt lgkmcnt(4)
	v_mfma_f32_32x32x16_bf16 v[32:47], v[240:243], v[104:107], v[32:47]
	v_add_f32_e32 v192, v192, v195
	s_waitcnt lgkmcnt(3)
	v_mfma_f32_32x32x16_bf16 v[32:47], v[244:247], v[108:111], v[32:47]
	v_max_f32_e32 v193, v80, v81
	v_max3_f32 v193, v193, v82, v83
	v_max3_f32 v193, v193, v84, v85
	v_max3_f32 v193, v193, v86, v87
	s_waitcnt lgkmcnt(2)
	v_mfma_f32_32x32x16_bf16 v[32:47], v[248:251], v[112:115], v[32:47]
	v_max3_f32 v193, v193, v88, v89
	v_max3_f32 v193, v193, v90, v91
	v_max3_f32 v193, v193, v92, v93
	v_max3_f32 v193, v193, v94, v95
	s_waitcnt lgkmcnt(1)
	v_mfma_f32_32x32x16_bf16 v[32:47], v[228:231], v[116:119], v[32:47]
	v_max3_f32 v193, v193, v64, v65
	v_max3_f32 v193, v193, v66, v67
	v_max3_f32 v193, v193, v68, v69
	v_max3_f32 v193, v193, v70, v71
	s_waitcnt lgkmcnt(0)
	v_mfma_f32_32x32x16_bf16 v[32:47], v[232:235], v[120:123], v[32:47]
	v_max3_f32 v193, v193, v72, v73
	v_max3_f32 v193, v193, v74, v75
	v_max3_f32 v193, v193, v76, v77
	v_max3_f32 v193, v193, v78, v79
	v_cmp_lt_f32_e32 vcc, 0x41000000, v193
	s_cbranch_vccz .LBB0_2730
	ds_bpermute_b32 v195, v186, v193
	s_waitcnt lgkmcnt(0)
	v_max_f32_e32 v195, v193, v195
	v_max_f32_e32 v195, 0, v195
	v_sub_f32_e32 v196, 0, v195
	v_exp_f32_e32 v196, v196
	s_nop 0
	v_mul_f32_e32 v192, v192, v196
	v_pk_mul_f32 v[30:31], v[30:31], v[196:197] op_sel_hi:[1,0]
	v_pk_mul_f32 v[28:29], v[28:29], v[196:197] op_sel_hi:[1,0]
	v_pk_mul_f32 v[26:27], v[26:27], v[196:197] op_sel_hi:[1,0]
	v_pk_mul_f32 v[24:25], v[24:25], v[196:197] op_sel_hi:[1,0]
	v_pk_mul_f32 v[22:23], v[22:23], v[196:197] op_sel_hi:[1,0]
	v_pk_mul_f32 v[20:21], v[20:21], v[196:197] op_sel_hi:[1,0]
	v_pk_mul_f32 v[18:19], v[18:19], v[196:197] op_sel_hi:[1,0]
	v_pk_mul_f32 v[16:17], v[16:17], v[196:197] op_sel_hi:[1,0]
	v_pk_mul_f32 v[14:15], v[14:15], v[196:197] op_sel_hi:[1,0]
	v_pk_mul_f32 v[12:13], v[12:13], v[196:197] op_sel_hi:[1,0]
	v_pk_mul_f32 v[10:11], v[10:11], v[196:197] op_sel_hi:[1,0]
	v_pk_mul_f32 v[8:9], v[8:9], v[196:197] op_sel_hi:[1,0]
	v_pk_mul_f32 v[6:7], v[6:7], v[196:197] op_sel_hi:[1,0]
	v_pk_mul_f32 v[4:5], v[4:5], v[196:197] op_sel_hi:[1,0]
	v_pk_mul_f32 v[2:3], v[2:3], v[196:197] op_sel_hi:[1,0]
	v_pk_mul_f32 v[0:1], v[0:1], v[196:197] op_sel_hi:[1,0]
	v_sub_f32_e32 v160, v160, v195
	v_sub_f32_e32 v161, v161, v195
	v_sub_f32_e32 v162, v162, v195
	v_sub_f32_e32 v163, v163, v195
	v_sub_f32_e32 v164, v164, v195
	v_sub_f32_e32 v165, v165, v195
	v_sub_f32_e32 v166, v166, v195
	v_sub_f32_e32 v167, v167, v195
	v_sub_f32_e32 v168, v168, v195
	v_sub_f32_e32 v169, v169, v195
	v_sub_f32_e32 v170, v170, v195
	v_sub_f32_e32 v171, v171, v195
	v_sub_f32_e32 v172, v172, v195
	v_sub_f32_e32 v173, v173, v195
	v_sub_f32_e32 v174, v174, v195
	v_sub_f32_e32 v175, v175, v195
	v_sub_f32_e32 v80, v80, v195
	v_sub_f32_e32 v81, v81, v195
	v_sub_f32_e32 v82, v82, v195
	v_sub_f32_e32 v83, v83, v195
	v_sub_f32_e32 v84, v84, v195
	v_sub_f32_e32 v85, v85, v195
	v_sub_f32_e32 v86, v86, v195
	v_sub_f32_e32 v87, v87, v195
	v_sub_f32_e32 v88, v88, v195
	v_sub_f32_e32 v89, v89, v195
	v_sub_f32_e32 v90, v90, v195
	v_sub_f32_e32 v91, v91, v195
	v_sub_f32_e32 v92, v92, v195
	v_sub_f32_e32 v93, v93, v195
	v_sub_f32_e32 v94, v94, v195
	v_sub_f32_e32 v95, v95, v195
	v_sub_f32_e32 v64, v64, v195
	v_sub_f32_e32 v65, v65, v195
	v_sub_f32_e32 v66, v66, v195
	v_sub_f32_e32 v67, v67, v195
	v_sub_f32_e32 v68, v68, v195
	v_sub_f32_e32 v69, v69, v195
	v_sub_f32_e32 v70, v70, v195
	v_sub_f32_e32 v71, v71, v195
	v_sub_f32_e32 v72, v72, v195
	v_sub_f32_e32 v73, v73, v195
	v_sub_f32_e32 v74, v74, v195
	v_sub_f32_e32 v75, v75, v195
	v_sub_f32_e32 v76, v76, v195
	v_sub_f32_e32 v77, v77, v195
	v_sub_f32_e32 v78, v78, v195
	v_sub_f32_e32 v79, v79, v195
	v_sub_f32_e32 v48, v48, v195
	v_sub_f32_e32 v49, v49, v195
	v_sub_f32_e32 v50, v50, v195
	v_sub_f32_e32 v51, v51, v195
	v_sub_f32_e32 v52, v52, v195
	v_sub_f32_e32 v53, v53, v195
	v_sub_f32_e32 v54, v54, v195
	v_sub_f32_e32 v55, v55, v195
	v_sub_f32_e32 v56, v56, v195
	v_sub_f32_e32 v57, v57, v195
	v_sub_f32_e32 v58, v58, v195
	v_sub_f32_e32 v59, v59, v195
	v_sub_f32_e32 v60, v60, v195
	v_sub_f32_e32 v61, v61, v195
	v_sub_f32_e32 v62, v62, v195
	v_sub_f32_e32 v63, v63, v195
	v_sub_f32_e32 v32, v32, v195
	v_sub_f32_e32 v33, v33, v195
	v_sub_f32_e32 v34, v34, v195
	v_sub_f32_e32 v35, v35, v195
	v_sub_f32_e32 v36, v36, v195
	v_sub_f32_e32 v37, v37, v195
	v_sub_f32_e32 v38, v38, v195
	v_sub_f32_e32 v39, v39, v195
	v_sub_f32_e32 v40, v40, v195
	v_sub_f32_e32 v41, v41, v195
	v_sub_f32_e32 v42, v42, v195
	v_sub_f32_e32 v43, v43, v195
	v_sub_f32_e32 v44, v44, v195
	v_sub_f32_e32 v45, v45, v195
	v_sub_f32_e32 v46, v46, v195
	v_sub_f32_e32 v47, v47, v195
.LBB0_2730:
	s_mul_i32 s4, s13, 0x2400
	v_add_u32_e32 v193, s4, v159
	v_exp_f32_e32 v80, v80
	v_exp_f32_e32 v81, v81
	v_add_u32_e32 v195, 0x9800, v193
	v_add_u32_e32 v193, 0xa800, v193
	v_exp_f32_e32 v82, v82
	v_exp_f32_e32 v83, v83
	ds_read_b64 v[196:197], v195 offset:1024
	ds_read_b64 v[198:199], v195 offset:1040
	ds_read_b64 v[200:201], v193 offset:1536
	ds_read_b64 v[202:203], v193 offset:1552
	v_exp_f32_e32 v84, v84
	v_exp_f32_e32 v85, v85
	v_exp_f32_e32 v86, v86
	v_exp_f32_e32 v87, v87
	ds_read_b64 v[204:205], v195 offset:1056
	ds_read_b64 v[206:207], v195 offset:1072
	ds_read_b64 v[208:209], v193 offset:1568
	ds_read_b64 v[210:211], v193 offset:1584
	v_cvt_pk_bf16_f32 v212, v80, v81
	v_cvt_pk_bf16_f32 v213, v82, v83
	v_cvt_pk_bf16_f32 v214, v84, v85
	v_exp_f32_e32 v88, v88
	v_cvt_pk_bf16_f32 v215, v86, v87
	v_exp_f32_e32 v89, v89
	v_exp_f32_e32 v90, v90
	v_exp_f32_e32 v91, v91
	s_waitcnt lgkmcnt(6)
	v_mfma_f32_32x32x16_bf16 v[16:31], v[196:199], v[212:215], v[16:31]
	v_pk_add_f32 v[220:221], v[80:81], v[82:83]
	v_pk_add_f32 v[222:223], v[84:85], v[86:87]
	v_exp_f32_e32 v92, v92
	v_exp_f32_e32 v93, v93
	s_waitcnt lgkmcnt(4)
	v_mfma_f32_32x32x16_bf16 v[0:15], v[200:203], v[212:215], v[0:15]
	v_exp_f32_e32 v94, v94
	v_exp_f32_e32 v95, v95
	ds_read_b64 v[196:197], v195 offset:1088
	ds_read_b64 v[198:199], v195 offset:1104
	ds_read_b64 v[200:201], v193 offset:1600
	ds_read_b64 v[202:203], v193 offset:1616
	v_cvt_pk_bf16_f32 v216, v88, v89
	v_cvt_pk_bf16_f32 v217, v90, v91
	v_cvt_pk_bf16_f32 v218, v92, v93
	v_exp_f32_e32 v64, v64
	v_cvt_pk_bf16_f32 v219, v94, v95
	v_exp_f32_e32 v65, v65
	v_exp_f32_e32 v66, v66
	v_exp_f32_e32 v67, v67
	s_waitcnt lgkmcnt(6)
	v_mfma_f32_32x32x16_bf16 v[16:31], v[204:207], v[216:219], v[16:31]
	v_pk_add_f32 v[220:221], v[220:221], v[88:89]
	v_pk_add_f32 v[222:223], v[222:223], v[90:91]
	v_exp_f32_e32 v68, v68
	v_exp_f32_e32 v69, v69
	s_waitcnt lgkmcnt(4)
	v_mfma_f32_32x32x16_bf16 v[0:15], v[208:211], v[216:219], v[0:15]
	v_pk_add_f32 v[220:221], v[220:221], v[92:93]
	v_pk_add_f32 v[222:223], v[222:223], v[94:95]
	v_exp_f32_e32 v70, v70
	v_exp_f32_e32 v71, v71
	ds_read_b64 v[204:205], v195 offset:1120
	ds_read_b64 v[206:207], v195 offset:1136
	ds_read_b64 v[208:209], v193 offset:1632
	ds_read_b64 v[210:211], v193 offset:1648
	v_cvt_pk_bf16_f32 v212, v64, v65
	v_cvt_pk_bf16_f32 v213, v66, v67
	v_cvt_pk_bf16_f32 v214, v68, v69
	v_exp_f32_e32 v72, v72
	v_cvt_pk_bf16_f32 v215, v70, v71
	v_exp_f32_e32 v73, v73
	v_exp_f32_e32 v74, v74
	v_exp_f32_e32 v75, v75
	s_waitcnt lgkmcnt(6)
	v_mfma_f32_32x32x16_bf16 v[16:31], v[196:199], v[212:215], v[16:31]
	v_pk_add_f32 v[220:221], v[220:221], v[64:65]
	v_pk_add_f32 v[222:223], v[222:223], v[66:67]
	v_exp_f32_e32 v76, v76
	v_exp_f32_e32 v77, v77
	s_waitcnt lgkmcnt(4)
	v_mfma_f32_32x32x16_bf16 v[0:15], v[200:203], v[212:215], v[0:15]
	v_pk_add_f32 v[220:221], v[220:221], v[68:69]
	v_pk_add_f32 v[222:223], v[222:223], v[70:71]
	v_exp_f32_e32 v78, v78
	v_exp_f32_e32 v79, v79
	v_cvt_pk_bf16_f32 v216, v72, v73
	v_cvt_pk_bf16_f32 v217, v74, v75
	v_cvt_pk_bf16_f32 v218, v76, v77
	v_pk_add_f32 v[220:221], v[220:221], v[72:73]
	v_cvt_pk_bf16_f32 v219, v78, v79
	v_pk_add_f32 v[222:223], v[222:223], v[74:75]
	s_add_i32 s16, s16, 2
	s_waitcnt lgkmcnt(2)
	v_mfma_f32_32x32x16_bf16 v[16:31], v[204:207], v[216:219], v[16:31]
	v_pk_add_f32 v[220:221], v[220:221], v[76:77]
	v_pk_add_f32 v[222:223], v[222:223], v[78:79]
	s_waitcnt lgkmcnt(0)
	v_mfma_f32_32x32x16_bf16 v[0:15], v[208:211], v[216:219], v[0:15]
	v_pk_add_f32 v[220:221], v[220:221], v[222:223]
	s_cmp_ge_u32 s18, s8
	v_add_f32_e32 v220, v220, v221
	v_add_f32_e32 v192, v192, v220
	s_cbranch_scc1 .LBB0_2693
	s_mov_b32 s4, s13
	s_mov_b32 s13, s12
	s_mov_b32 s12, s17
	s_branch .LBB0_2710
